# v9 plus row-sum via packed f32 adds (15 v_pk_add_f32 + 2 adds instead of 32 dependent adds)
# speedup vs baseline: 1.0029x; 1.0029x over previous
; template <int DQK, int MODE, bool PIPE>
; DI void attn_core(const u16* __restrict__ Qg, const u16* __restrict__ Kg, const u16* __restrict__ Vtg, int ntiles,
;                   int kr_lo, int rs, int r_q, int c_q, int cs, const float* biasL, char* lds, f32x16 (&o)[4], float& l_out, int tid) {
;     ...
;     for (int i = 0; i < 16; ++i) { p0[i] = __builtin_amdgcn_exp2f(p0[i]); p1[i] = __builtin_amdgcn_exp2f(p1[i]); ps += p0[i] + p1[i]; }
;     l += ps;
;     ...
;       if (t + 1 < ntiles) swriteK((t + 1) & 1);
;       if (t + 2 < ntiles) gloadK(t + 2);
;     }
;     __syncthreads();
;   };
.LBB0_829:
	v_pk_add_f32 v[250:251], v[66:67], v[82:83]
	v_pk_add_f32 v[250:251], v[250:251], v[68:69]
	v_pk_add_f32 v[250:251], v[250:251], v[70:71]
	v_pk_add_f32 v[250:251], v[250:251], v[72:73]
	v_pk_add_f32 v[250:251], v[250:251], v[74:75]
	v_pk_add_f32 v[250:251], v[250:251], v[76:77]
	v_pk_add_f32 v[250:251], v[250:251], v[78:79]
	v_pk_add_f32 v[250:251], v[250:251], v[80:81]
	v_pk_add_f32 v[250:251], v[250:251], v[84:85]
	v_pk_add_f32 v[250:251], v[250:251], v[86:87]
	v_pk_add_f32 v[250:251], v[250:251], v[88:89]
	v_pk_add_f32 v[250:251], v[250:251], v[90:91]
	v_pk_add_f32 v[250:251], v[250:251], v[92:93]
	v_pk_add_f32 v[250:251], v[250:251], v[94:95]
	v_pk_add_f32 v[250:251], v[250:251], v[96:97]
	v_add_f32_e32 v222, v222, v250
	v_add_f32_e32 v222, v222, v251
	s_add_u32 s0, s0, 0x6000
	s_addc_u32 s1, s1, 0
	v_lshl_add_u64 v[176:177], v[176:177], 0, s[2:3]
	s_cmp_lg_u32 s17, s18
	v_lshl_add_u64 v[218:219], v[218:219], 0, s[2:3]
	s_waitcnt lgkmcnt(0)
	s_barrier
	s_cbranch_scc0 .LBB0_831
	s_mov_b32 s6, s18
	s_branch .LBB0_817

; template <int DQK, int MODE, bool PIPE>
; DI void attn_core(const u16* __restrict__ Qg, const u16* __restrict__ Kg, const u16* __restrict__ Vtg, int ntiles,
;                   int kr_lo, int rs, int r_q, int c_q, int cs, const float* biasL, char* lds, f32x16 (&o)[4], float& l_out, int tid) {
;     ...
;     for (int i = 0; i < 16; ++i) { p0[i] = __builtin_amdgcn_exp2f(p0[i]); p1[i] = __builtin_amdgcn_exp2f(p1[i]); ps += p0[i] + p1[i]; }
;     l += ps;
;     ...
;       if (t + 1 < ntiles) swriteK((t + 1) & 1);
;       if (t + 2 < ntiles) gloadK(t + 2);
;     }
;     __syncthreads();
;   };
.LBB0_848:
	v_pk_add_f32 v[236:237], v[82:83], v[98:99]
	v_pk_add_f32 v[236:237], v[236:237], v[84:85]
	v_pk_add_f32 v[236:237], v[236:237], v[86:87]
	v_pk_add_f32 v[236:237], v[236:237], v[88:89]
	v_pk_add_f32 v[236:237], v[236:237], v[90:91]
	v_pk_add_f32 v[236:237], v[236:237], v[92:93]
	v_pk_add_f32 v[236:237], v[236:237], v[94:95]
	v_pk_add_f32 v[236:237], v[236:237], v[96:97]
	v_pk_add_f32 v[236:237], v[236:237], v[100:101]
	v_pk_add_f32 v[236:237], v[236:237], v[102:103]
	v_pk_add_f32 v[236:237], v[236:237], v[104:105]
	v_pk_add_f32 v[236:237], v[236:237], v[106:107]
	v_pk_add_f32 v[236:237], v[236:237], v[108:109]
	v_pk_add_f32 v[236:237], v[236:237], v[110:111]
	v_pk_add_f32 v[236:237], v[236:237], v[112:113]
	v_add_f32_e32 v176, v176, v236
	v_add_f32_e32 v176, v176, v237
	v_lshl_add_u64 v[144:145], v[144:145], 0, s[44:45]
	v_lshl_add_u64 v[162:163], v[162:163], 0, s[2:3]
	s_cmp_lg_u32 s10, s14
	v_lshl_add_u64 v[150:151], v[150:151], 0, s[2:3]
	s_waitcnt lgkmcnt(0)
	s_barrier
	s_cbranch_scc0 .LBB0_850
	s_mov_b32 s15, s14
	s_branch .LBB0_838

; template <int DQK, int MODE, bool PIPE>
; DI void attn_core(const u16* __restrict__ Qg, const u16* __restrict__ Kg, const u16* __restrict__ Vtg, int ntiles,
;                   int kr_lo, int rs, int r_q, int c_q, int cs, const float* biasL, char* lds, f32x16 (&o)[4], float& l_out, int tid) {
;     ...
;     for (int i = 0; i < 16; ++i) { p0[i] = __builtin_amdgcn_exp2f(p0[i]); p1[i] = __builtin_amdgcn_exp2f(p1[i]); ps += p0[i] + p1[i]; }
;     l += ps;
;     ...
;       if (t + 1 < ntiles) swriteK((t + 1) & 1);
;       if (t + 2 < ntiles) gloadK(t + 2);
;     }
;     __syncthreads();
;   };
.LBB0_864:
	v_pk_add_f32 v[236:237], v[82:83], v[98:99]
	v_pk_add_f32 v[236:237], v[236:237], v[84:85]
	v_pk_add_f32 v[236:237], v[236:237], v[86:87]
	v_pk_add_f32 v[236:237], v[236:237], v[88:89]
	v_pk_add_f32 v[236:237], v[236:237], v[90:91]
	v_pk_add_f32 v[236:237], v[236:237], v[92:93]
	v_pk_add_f32 v[236:237], v[236:237], v[94:95]
	v_pk_add_f32 v[236:237], v[236:237], v[96:97]
	v_pk_add_f32 v[236:237], v[236:237], v[100:101]
	v_pk_add_f32 v[236:237], v[236:237], v[102:103]
	v_pk_add_f32 v[236:237], v[236:237], v[104:105]
	v_pk_add_f32 v[236:237], v[236:237], v[106:107]
	v_pk_add_f32 v[236:237], v[236:237], v[108:109]
	v_pk_add_f32 v[236:237], v[236:237], v[110:111]
	v_pk_add_f32 v[236:237], v[236:237], v[112:113]
	v_add_f32_e32 v155, v155, v236
	v_add_f32_e32 v155, v155, v237
	v_lshl_add_u64 v[152:153], v[152:153], 0, s[44:45]
	v_lshl_add_u64 v[146:147], v[146:147], 0, s[2:3]
	s_cmp_lg_u32 s10, s11
	v_lshl_add_u64 v[148:149], v[148:149], 0, s[2:3]
	s_waitcnt lgkmcnt(0)
	s_barrier
	s_cbranch_scc0 .LBB0_866
	s_mov_b32 s12, s11
	s_branch .LBB0_854
